# bank-conflict-free slot permutation of the 8 shifted Toeplitz filter copies in LDS (hyena latent + context units), on top of v18
# speedup vs baseline: 1.0049x; 1.0049x over previous
.LBB0_459:
	s_andn2_b64 vcc, exec, s[0:1]
	s_cbranch_vccnz .LBB0_527
	v_ashrrev_i32_e32 v2, 2, v130
	v_ashrrev_i32_e32 v131, 31, v130
	v_bfi_b32 v7, -16, v2, v130
	v_lshrrev_b32_e32 v2, 30, v131
	v_add_u32_e32 v2, v7, v2
	v_ashrrev_i32_e32 v2, 2, v2
	s_lshl_b32 s0, s9, 1
	v_bfe_u32 v1, v130, 4, 2
	s_add_i32 s28, s0, 0xfffffc80
	v_ashrrev_i32_e32 v3, 31, v2
	s_movk_i32 s0, 0x1c0
	v_lshlrev_b64 v[4:5], 20, v[2:3]
	v_cmp_gt_i32_e64 s[40:41], s0, v130
	v_and_b32_e32 v3, 7, v130
	v_and_b32_e32 v108, 3, v3
	v_lshrrev_b32_e32 v109, 2, v3
	v_lshl_add_u32 v108, v108, 1, 1
	v_sub_u32_e32 v3, v108, v109
	s_waitcnt vmcnt(0)
	v_lshl_add_u32 v53, v1, 4, 0
	s_movk_i32 s0, 0x420
	s_waitcnt vmcnt(0)
	v_lshlrev_b32_e32 v18, 2, v1
	v_lshlrev_b32_e32 v11, 3, v1
	v_mad_u32_u24 v1, v3, s0, v53
	v_and_b32_e32 v3, 8, v130
	v_lshlrev_b32_e32 v3, 1, v3
	v_lshlrev_b32_e32 v12, 8, v2
	v_lshrrev_b32_e32 v2, 27, v131
	v_sub_u32_e32 v54, v1, v3
	v_add_u32_e32 v3, v130, v2
	v_ashrrev_i32_e32 v2, 5, v3
	v_and_b32_e32 v3, 0xffffffe0, v3
	v_sub_u32_e32 v8, v130, v3
	v_lshlrev_b32_e32 v20, 3, v8
	v_ashrrev_i32_e32 v3, 3, v8
	s_movk_i32 s0, 0x110
	v_lshl_add_u32 v9, v2, 2, v3
	v_and_b32_e32 v13, 56, v20
	v_cmp_lt_i32_e64 s[42:43], 0, v8
	v_cmp_gt_i32_e64 s[44:45], 31, v8
	v_mul_lo_u32 v8, v9, s0
	v_mul_lo_u32 v15, v9, s21
	v_lshlrev_b32_e32 v9, 2, v13
	v_add_u32_e32 v19, 0x200, v130
	v_add3_u32 v57, 0, v8, v9
	v_ashrrev_i32_e32 v8, 31, v19
	v_lshrrev_b32_e32 v8, 27, v8
	v_add_u32_e32 v9, v19, v8
	v_ashrrev_i32_e32 v8, 5, v9
	v_and_b32_e32 v9, 0xffffffe0, v9
	v_lshl_add_u32 v14, v13, 1, 0
	v_sub_u32_e32 v13, v19, v9
	v_lshlrev_b32_e32 v24, 3, v13
	v_ashrrev_i32_e32 v9, 3, v13
	v_and_b32_e32 v10, 3, v130
	v_lshl_add_u32 v16, v8, 2, v9
	v_and_b32_e32 v17, 56, v24
	v_cmp_lt_i32_e64 s[46:47], 0, v13
	v_cmp_gt_i32_e64 s[48:49], 31, v13
	v_lshl_add_u32 v13, v17, 1, 0
	v_mul_lo_u32 v28, v16, s0
	v_lshlrev_b32_e32 v17, 2, v17
	v_cmp_gt_u32_e64 s[52:53], 2, v10
	v_add3_u32 v58, 0, v28, v17
	v_cmp_ne_u32_e64 s[54:55], 3, v10
	v_cndmask_b32_e64 v28, 0, 2, s[52:53]
	v_add_u32_e32 v28, v28, v7
	v_mul_lo_u32 v35, v28, s21
	v_addc_co_u32_e64 v28, vcc, 0, v7, s[54:55]
	v_cmp_ne_u32_e64 s[56:57], 0, v10
	v_cmp_eq_u32_e64 s[50:51], 0, v10
	v_mul_lo_u32 v37, v28, s21
	v_subbrev_co_u32_e64 v28, vcc, 0, v7, s[56:57]
	v_cmp_lt_u32_e64 s[58:59], 1, v10
	v_cmp_eq_u32_e64 s[60:61], 3, v10
	v_lshlrev_b32_e32 v6, 6, v10
	v_cndmask_b32_e64 v17, 0, 3, s[50:51]
	v_mul_lo_u32 v38, v28, s21
	v_cndmask_b32_e64 v28, 0, -2, s[58:59]
	v_cndmask_b32_e64 v10, 0, -3, s[60:61]
	v_mul_lo_u32 v55, v7, s21
	v_mul_lo_u32 v56, v7, s0
	v_add_u32_e32 v17, v17, v7
	v_add_u32_e32 v28, v28, v7
	v_add_u32_e32 v7, v10, v7
	v_or3_b32 v10, v12, v6, v18
	v_readlane_b32 s0, v254, 14
	v_ashrrev_i32_e32 v3, 31, v2
	v_ashrrev_i32_e32 v9, 31, v8
	v_mul_lo_u32 v16, v16, s21
	v_mul_lo_u32 v17, v17, s21
	v_mul_lo_u32 v39, v28, s21
	v_mul_lo_u32 v7, v7, s21
	v_lshlrev_b32_e32 v60, 2, v10
	v_readlane_b32 s1, v254, 15
	v_cmp_gt_i32_e64 s[38:39], 64, v130
	v_lshlrev_b32_e32 v52, 4, v130
	v_add_u32_e32 v52, 0x420, v52
	v_mov_b32_e32 v1, v130
	v_ashrrev_i32_e32 v21, 31, v20
	s_mov_b32 s29, 0
	v_mov_b32_e32 v22, v20
	v_mov_b32_e32 v23, v0
	v_ashrrev_i32_e32 v25, 31, v24
	v_mov_b32_e32 v26, v24
	v_mov_b32_e32 v27, v0
	v_add3_u32 v59, 0, v55, v11
	v_or_b32_e32 v61, 64, v60
	v_or_b32_e32 v62, 0x80, v60
	v_or_b32_e32 v63, 0xc0, v60
	v_lshlrev_b64 v[28:29], 20, v[2:3]
	v_lshlrev_b64 v[30:31], 20, v[8:9]
	v_lshl_add_u64 v[32:33], s[0:1], 0, v[4:5]
	s_mov_b64 s[0:1], -1
	v_lshlrev_b32_e32 v34, 1, v6
	v_lshlrev_b32_e32 v36, 1, v18
	v_add_u32_e32 v64, v14, v15
	v_add_u32_e32 v65, v13, v16
	v_add_u32_e32 v66, v53, v17
	v_add_u32_e32 v67, v53, v35
	v_add_u32_e32 v68, v53, v37
	v_add_u32_e32 v69, v53, v38
	v_add_u32_e32 v70, v53, v39
	v_add_u32_e32 v71, v53, v7
	s_branch .LBB0_462

.LBB0_494:
	s_or_b64 exec, exec, s[22:23]
	v_add_u32_e32 v13, 1, v13
	v_and_b32_e32 v108, 3, v13
	v_lshrrev_b32_e32 v13, 2, v13
	v_lshl_add_u32 v108, v108, 1, 1
	v_sub_u32_e32 v13, v108, v13
	v_mul_u32_u24_e32 v13, 0x420, v13
	v_and_b32_e32 v108, 63, v12
	v_lshl_add_u32 v13, v108, 4, v13
	s_movk_i32 s22, 0xffbf
	s_waitcnt lgkmcnt(0)
	ds_write_b128 v13, v[6:9]
	v_add_u32_e32 v6, 0x200, v12
	v_cmp_lt_i32_e32 vcc, s22, v12
	v_add_u32_e32 v10, 0x800, v10
	v_add_u32_e32 v11, 0x2000, v11
	s_or_b64 s[16:17], vcc, s[16:17]
	v_mov_b32_e32 v12, v6
	s_andn2_b64 exec, exec, s[16:17]
	s_cbranch_execz .LBB0_499
.LBB0_495:
	v_ashrrev_i32_e32 v6, 31, v12
	v_lshrrev_b32_e32 v6, 26, v6
	v_add_u32_e32 v6, v12, v6
	v_ashrrev_i32_e32 v13, 6, v6
	v_add_u32_e32 v6, 2, v13
	v_ashrrev_i32_e32 v6, 1, v6
	v_lshl_add_u32 v6, v13, 8, v6
	v_sub_u32_e32 v14, v10, v6
	v_max_i32_e32 v6, 0, v14
	v_max_i32_e32 v7, -1, v14
	v_max_i32_e32 v8, -2, v14
	v_max_i32_e32 v9, -3, v14
	v_lshl_add_u32 v6, v6, 2, 0
	v_lshl_add_u32 v7, v7, 2, 0
	v_lshl_add_u32 v8, v8, 2, 0
	v_lshl_add_u32 v9, v9, 2, 0
	ds_read_b32 v6, v6 offset:1056
	ds_read_b32 v7, v7 offset:1060
	ds_read_b32 v8, v8 offset:1064
	ds_read_b32 v9, v9 offset:1068
	v_and_b32_e32 v15, 1, v13
	v_cmp_eq_u32_e32 vcc, 1, v15
	s_and_saveexec_b64 s[22:23], vcc
	s_xor_b64 s[22:23], exec, s[22:23]
	s_andn2_saveexec_b64 s[22:23], s[22:23]
	s_cbranch_execz .LBB0_494
	v_max_i32_e32 v14, -4, v14
	v_lshl_add_u32 v14, v14, 2, 0
	ds_read_b32 v14, v14 offset:1072
	s_waitcnt lgkmcnt(3)
	v_perm_b32 v6, v6, v7, s33
	s_waitcnt lgkmcnt(2)
	v_perm_b32 v7, v7, v8, s33
	s_waitcnt lgkmcnt(1)
	v_perm_b32 v8, v8, v9, s33
	s_waitcnt lgkmcnt(0)
	v_perm_b32 v9, v9, v14, s33
	s_branch .LBB0_494

.LBB0_738:
	v_ashrrev_i32_e32 v131, 31, v130
	v_add_u32_sdwa v6, v130, v131 dst_sel:DWORD dst_unused:UNUSED_PAD src0_sel:DWORD src1_sel:BYTE_3
	v_ashrrev_i32_e32 v6, 8, v6
	v_mul_i32_i24_e32 v7, 0x100, v6
	v_sub_u32_e32 v11, v130, v7
	v_bfe_u32 v1, v130, 6, 2
	v_ashrrev_i32_e32 v7, 3, v11
	s_movk_i32 s2, 0xff
	v_lshrrev_b32_e32 v3, 6, v130
	v_and_b32_e32 v2, 15, v130
	v_lshlrev_b32_e32 v4, 4, v1
	v_lshl_add_u32 v12, v6, 5, v7
	v_cmp_gt_i32_e64 s[42:43], s2, v11
	s_movk_i32 s2, 0x110
	v_bitop3_b32 v9, v4, 31, v2 bitop3:0xc8
	v_bfe_u32 v10, v3, 1, 1
	v_lshlrev_b32_e32 v14, 3, v11
	s_waitcnt vmcnt(0)
	v_mul_lo_u32 v24, v12, s2
	s_movk_i32 s2, 0xe00
	v_or_b32_e32 v1, v4, v2
	v_lshlrev_b32_e32 v19, 22, v10
	v_lshlrev_b32_e32 v2, 6, v9
	v_and_b32_e32 v13, 56, v14
	v_cmp_gt_i32_e64 s[44:45], s2, v130
	v_lshlrev_b32_e32 v10, 14, v10
	v_lshlrev_b32_e32 v9, 9, v9
	v_readlane_b32 s2, v252, 1
	v_ashrrev_i32_e32 v7, 31, v6
	v_bfe_u32 v5, v130, 4, 2
	v_add3_u32 v47, s2, v10, v9
	v_lshlrev_b32_e32 v10, 2, v13
	v_readlane_b32 s2, v252, 2
	v_ashrrev_i32_e32 v8, 7, v130
	v_lshlrev_b64 v[6:7], 23, v[6:7]
	v_add3_u32 v48, s2, v24, v10
	v_readlane_b32 s2, v252, 3
	v_lshlrev_b32_e32 v4, 2, v5
	v_readlane_b32 s3, v252, 0
	v_lshlrev_b32_e32 v18, 4, v3
	v_and_b32_e32 v28, 7, v130
	v_and_b32_e32 v80, 3, v28
	v_lshrrev_b32_e32 v81, 2, v28
	v_lshl_add_u32 v80, v80, 1, 1
	v_sub_u32_e32 v28, v80, v81
	v_lshlrev_b32_e32 v5, 4, v5
	v_lshlrev_b32_e32 v9, 4, v8
	v_add3_u32 v49, s2, v24, v10
	v_lshl_add_u64 v[24:25], s[78:79], 0, v[6:7]
	s_movk_i32 s2, 0x2020
	v_lshlrev_b32_e32 v6, 1, v130
	v_or_b32_e32 v26, 0xffffffe1, v18
	v_and_or_b32 v44, v18, 16, 15
	v_add_u32_e32 v18, s3, v5
	v_and_b32_e32 v20, 0xffffffe0, v9
	v_or_b32_e32 v9, 1, v8
	v_mad_u32_u24 v5, v28, s2, v5
	v_and_b32_e32 v6, 16, v6
	v_sub_u32_e32 v5, v5, v6
	v_lshlrev_b32_e32 v6, 5, v9
	v_sub_u32_e32 v6, v5, v6
	v_lshlrev_b32_e32 v7, 7, v26
	v_sub_u32_e32 v6, v6, v7
	s_add_i32 s2, 0, 0x1000
	v_add_u32_e32 v57, s2, v6
	v_lshlrev_b32_e32 v6, 5, v8
	v_and_b32_e32 v6, 0xffffffc0, v6
	v_lshlrev_b16_e32 v3, 4, v3
	v_cmp_lt_i32_e64 s[40:41], 0, v11
	v_mov_b32_e32 v11, s3
	v_lshlrev_b32_e32 v22, 4, v9
	v_sub_u32_e32 v5, v5, v6
	v_bitop3_b16 v3, v3, v130, 15 bitop3:0xf8
	s_lshl_b32 s0, s9, 2
	s_movk_i32 s1, 0x200
	v_lshl_add_u32 v27, v13, 1, s3
	v_mul_lo_u32 v12, v12, s21
	v_mad_u32_u24 v11, v1, s21, v11
	v_or_b32_e32 v50, v20, v4
	v_or_b32_e32 v53, v22, v4
	v_sub_u32_e32 v5, v5, v7
	v_and_b32_e32 v3, 31, v3
	s_addk_i32 s0, 0xff00
	v_cmp_gt_i32_e64 s[38:39], s1, v130
	v_ashrrev_i32_e32 v15, 31, v14
	s_mov_b32 s1, 0
	v_mov_b32_e32 v16, v14
	v_mov_b32_e32 v17, v0
	v_lshlrev_b32_e32 v45, 4, v130
	v_add_u32_e32 v45, 0x2020, v45
	v_mul_u32_u24_e32 v46, 0x110, v1
	v_ashrrev_i32_e32 v21, 31, v20
	v_ashrrev_i32_e32 v23, 31, v22
	v_lshl_add_u32 v51, v50, 1, v11
	v_lshlrev_b32_e32 v52, 3, v50
	v_lshl_add_u32 v54, v53, 1, v11
	v_lshlrev_b32_e32 v55, 3, v53
	v_add_u32_e32 v56, -1, v26
	v_add_u32_e32 v58, s2, v5
	v_sub_u32_e32 v59, v3, v26
	v_lshlrev_b32_e32 v26, 1, v2
	v_lshlrev_b32_e32 v28, 1, v4
	v_add_u32_e32 v60, v27, v12
	s_branch .LBB0_740

.LBB0_760:
	s_or_b64 exec, exec, s[22:23]
	v_add_u32_e32 v13, 1, v13
	v_and_b32_e32 v38, 3, v13
	v_lshrrev_b32_e32 v13, 2, v13
	v_lshl_add_u32 v38, v38, 1, 1
	v_sub_u32_e32 v13, v38, v13
	v_mul_u32_u24_e32 v13, 0x2020, v13
	v_and_b32_e32 v38, 0x1ff, v12
	v_lshl_add_u32 v13, v38, 4, v13
	s_movk_i32 s22, 0xbff
	s_waitcnt lgkmcnt(0)
	ds_write_b128 v13, v[6:9]
	v_add_u32_e32 v6, 0x200, v12
	v_cmp_lt_i32_e32 vcc, s22, v12
	v_add_u32_e32 v10, 0x800, v10
	v_add_u32_e32 v11, 0x2000, v11
	s_or_b64 s[16:17], vcc, s[16:17]
	v_mov_b32_e32 v12, v6
	s_andn2_b64 exec, exec, s[16:17]
	s_cbranch_execz .LBB0_765
.LBB0_761:
	v_ashrrev_i32_e32 v6, 31, v12
	v_lshrrev_b32_e32 v6, 23, v6
	v_add_u32_e32 v6, v12, v6
	v_ashrrev_i32_e32 v13, 9, v6
	v_add_u32_e32 v6, 2, v13
	v_mul_i32_i24_e32 v38, 0x200, v13
	v_ashrrev_i32_e32 v6, 1, v6
	v_lshl_add_u32 v6, v38, 2, v6
	v_sub_u32_e32 v39, v10, v6
	v_max_i32_e32 v6, 0, v39
	v_max_i32_e32 v7, -1, v39
	v_max_i32_e32 v8, -2, v39
	v_max_i32_e32 v9, -3, v39
	v_lshl_add_u32 v6, v6, 2, 0
	v_lshl_add_u32 v7, v7, 2, 0
	v_lshl_add_u32 v8, v8, 2, 0
	v_lshl_add_u32 v9, v9, 2, 0
	ds_read_b32 v6, v6 offset:8224
	ds_read_b32 v7, v7 offset:8228
	ds_read_b32 v8, v8 offset:8232
	ds_read_b32 v9, v9 offset:8236
	v_and_b32_e32 v40, 1, v13
	v_cmp_eq_u32_e32 vcc, 1, v40
	s_and_saveexec_b64 s[22:23], vcc
	s_xor_b64 s[22:23], exec, s[22:23]
	s_andn2_saveexec_b64 s[22:23], s[22:23]
	s_cbranch_execz .LBB0_760
	v_max_i32_e32 v39, -4, v39
	v_lshl_add_u32 v39, v39, 2, 0
	ds_read_b32 v39, v39 offset:8240
	s_waitcnt lgkmcnt(3)
	v_perm_b32 v6, v6, v7, s33
	s_waitcnt lgkmcnt(2)
	v_perm_b32 v7, v7, v8, s33
	s_waitcnt lgkmcnt(1)
	v_perm_b32 v8, v8, v9, s33
	s_waitcnt lgkmcnt(0)
	v_perm_b32 v9, v9, v39, s33
	s_branch .LBB0_760
